# GEMM loops: 32-MFMA super-phase snake, m-major (activation-fragment operand shared at 12 of 15 pair boundaries, weight fragment at 3), mid-block setprio flip removed
# speedup vs baseline: 1.0053x; 1.0053x over previous
.LBB0_178:
	s_add_u32 s26, s22, 0xfffc0080
	s_addc_u32 s27, s23, -1
	s_add_i32 s34, 0, 0x10000
	s_cmp_eq_u32 s59, 12
	s_cselect_b32 s31, s9, s27
	s_cselect_b32 s30, s15, s26
	s_cselect_b32 s27, s13, s58
	s_cselect_b32 s26, s56, s57
	s_add_i32 s35, 0, 0x14000
	v_add_u32_e32 v140, s34, v195
	v_add_u32_e32 v166, s35, v195
	ds_read_b128 v[128:131], v140
	ds_read_b128 v[132:135], v140 offset:1024
	ds_read_b128 v[136:139], v140 offset:2048
	ds_read_b128 v[140:143], v140 offset:3072
	ds_read_b128 v[144:147], v166
	ds_read_b128 v[148:151], v166 offset:1024
	ds_read_b128 v[180:183], v166 offset:2048
	ds_read_b128 v[184:187], v166 offset:3072
	s_add_i32 m0, s49, 0xc000
	ds_read_b128 v[188:191], v200
	ds_read_b128 v[202:205], v200 offset:1024
	ds_read_b128 v[206:209], v200 offset:2048
	ds_read_b128 v[210:213], v200 offset:3072
	ds_read_b128 v[228:231], v200 offset:4096
	ds_read_b128 v[232:235], v200 offset:5120
	ds_read_b128 v[236:239], v200 offset:6144
	ds_read_b128 v[240:243], v200 offset:7168
	global_load_lds_dwordx4 v160, s[22:23]
	s_add_i32 m0, s49, 0xe000
	s_nop 0
	global_load_lds_dwordx4 v162, s[22:23]
	s_waitcnt vmcnt(8)
	s_waitcnt lgkmcnt(0)
	s_barrier
	s_setprio 1
	s_waitcnt lgkmcnt(0)
	v_mfma_f32_16x16x32_bf16 v[124:127], v[128:131], v[188:191], v[124:127]
	v_mfma_f32_16x16x32_bf16 v[124:127], v[132:135], v[202:205], v[124:127]
	v_mfma_f32_16x16x32_bf16 v[120:123], v[140:143], v[202:205], v[120:123]
	v_mfma_f32_16x16x32_bf16 v[120:123], v[136:139], v[188:191], v[120:123]
	v_mfma_f32_16x16x32_bf16 v[116:119], v[144:147], v[188:191], v[116:119]
	v_mfma_f32_16x16x32_bf16 v[116:119], v[148:151], v[202:205], v[116:119]
	v_mfma_f32_16x16x32_bf16 v[108:111], v[184:187], v[202:205], v[108:111]
	v_mfma_f32_16x16x32_bf16 v[108:111], v[180:183], v[188:191], v[108:111]
	v_mfma_f32_16x16x32_bf16 v[92:95], v[180:183], v[206:209], v[92:95]
	v_mfma_f32_16x16x32_bf16 v[92:95], v[184:187], v[210:213], v[92:95]
	v_mfma_f32_16x16x32_bf16 v[100:103], v[148:151], v[210:213], v[100:103]
	v_mfma_f32_16x16x32_bf16 v[100:103], v[144:147], v[206:209], v[100:103]
	v_mfma_f32_16x16x32_bf16 v[104:107], v[136:139], v[206:209], v[104:107]
	v_mfma_f32_16x16x32_bf16 v[104:107], v[140:143], v[210:213], v[104:107]
	v_mfma_f32_16x16x32_bf16 v[112:115], v[132:135], v[210:213], v[112:115]
	v_mfma_f32_16x16x32_bf16 v[112:115], v[128:131], v[206:209], v[112:115]
	v_mfma_f32_16x16x32_bf16 v[96:99], v[128:131], v[228:231], v[96:99]
	v_mfma_f32_16x16x32_bf16 v[96:99], v[132:135], v[232:235], v[96:99]
	v_mfma_f32_16x16x32_bf16 v[88:91], v[140:143], v[232:235], v[88:91]
	v_mfma_f32_16x16x32_bf16 v[88:91], v[136:139], v[228:231], v[88:91]
	v_mfma_f32_16x16x32_bf16 v[84:87], v[144:147], v[228:231], v[84:87]
	v_mfma_f32_16x16x32_bf16 v[84:87], v[148:151], v[232:235], v[84:87]
	v_mfma_f32_16x16x32_bf16 v[76:79], v[184:187], v[232:235], v[76:79]
	v_mfma_f32_16x16x32_bf16 v[76:79], v[180:183], v[228:231], v[76:79]
	v_mfma_f32_16x16x32_bf16 v[64:67], v[180:183], v[236:239], v[64:67]
	v_mfma_f32_16x16x32_bf16 v[64:67], v[184:187], v[240:243], v[64:67]
	v_mfma_f32_16x16x32_bf16 v[68:71], v[148:151], v[240:243], v[68:71]
	v_mfma_f32_16x16x32_bf16 v[68:71], v[144:147], v[236:239], v[68:71]
	v_mfma_f32_16x16x32_bf16 v[72:75], v[136:139], v[236:239], v[72:75]
	v_mfma_f32_16x16x32_bf16 v[72:75], v[140:143], v[240:243], v[72:75]
	v_mfma_f32_16x16x32_bf16 v[80:83], v[132:135], v[240:243], v[80:83]
	v_mfma_f32_16x16x32_bf16 v[80:83], v[128:131], v[236:239], v[80:83]
	s_setprio 0
	s_barrier
	s_add_i32 s34, s34, s45
	s_add_u32 s98, s26, s20
	s_addc_u32 s99, s27, s21
	s_mov_b32 m0, s34
	ds_read_b128 v[188:191], v200 offset:16384
	ds_read_b128 v[202:205], v200 offset:17408
	ds_read_b128 v[206:209], v200 offset:18432
	ds_read_b128 v[210:213], v200 offset:19456
	ds_read_b128 v[228:231], v200 offset:20480
	ds_read_b128 v[232:235], v200 offset:21504
	ds_read_b128 v[236:239], v200 offset:22528
	ds_read_b128 v[240:243], v200 offset:23552
	global_load_lds_dwordx4 v168, s[26:27]
	s_add_i32 m0, s34, 0x2000
	s_add_u32 s36, s26, 0x40000
	s_addc_u32 s37, s27, 0
	s_add_i32 s34, s35, s45
	global_load_lds_dwordx4 v152, s[26:27]
	s_mov_b32 m0, s34
	s_nop 0
	global_load_lds_dwordx4 v168, s[36:37]
	s_add_i32 m0, s34, 0x2000
	s_nop 0
	global_load_lds_dwordx4 v152, s[36:37]
	s_add_u32 s100, s30, s20
	s_addc_u32 s101, s31, s21
	s_mov_b32 m0, s49
	s_nop 0
	global_load_lds_dwordx4 v156, s[30:31]
	s_mov_b32 m0, s50
	s_nop 0
	global_load_lds_dwordx4 v154, s[30:31]
	s_waitcnt vmcnt(8)
	s_waitcnt lgkmcnt(0)
	s_barrier
	s_setprio 1
	s_waitcnt lgkmcnt(0)
	v_mfma_f32_16x16x32_bf16 v[60:63], v[128:131], v[188:191], v[60:63]
	v_mfma_f32_16x16x32_bf16 v[60:63], v[132:135], v[202:205], v[60:63]
	v_mfma_f32_16x16x32_bf16 v[56:59], v[140:143], v[202:205], v[56:59]
	v_mfma_f32_16x16x32_bf16 v[56:59], v[136:139], v[188:191], v[56:59]
	v_mfma_f32_16x16x32_bf16 v[52:55], v[144:147], v[188:191], v[52:55]
	v_mfma_f32_16x16x32_bf16 v[52:55], v[148:151], v[202:205], v[52:55]
	v_mfma_f32_16x16x32_bf16 v[44:47], v[184:187], v[202:205], v[44:47]
	v_mfma_f32_16x16x32_bf16 v[44:47], v[180:183], v[188:191], v[44:47]
	v_mfma_f32_16x16x32_bf16 v[28:31], v[180:183], v[206:209], v[28:31]
	v_mfma_f32_16x16x32_bf16 v[28:31], v[184:187], v[210:213], v[28:31]
	v_mfma_f32_16x16x32_bf16 v[36:39], v[148:151], v[210:213], v[36:39]
	v_mfma_f32_16x16x32_bf16 v[36:39], v[144:147], v[206:209], v[36:39]
	v_mfma_f32_16x16x32_bf16 v[40:43], v[136:139], v[206:209], v[40:43]
	v_mfma_f32_16x16x32_bf16 v[40:43], v[140:143], v[210:213], v[40:43]
	v_mfma_f32_16x16x32_bf16 v[48:51], v[132:135], v[210:213], v[48:51]
	v_mfma_f32_16x16x32_bf16 v[48:51], v[128:131], v[206:209], v[48:51]
	v_mfma_f32_16x16x32_bf16 v[32:35], v[128:131], v[228:231], v[32:35]
	v_mfma_f32_16x16x32_bf16 v[32:35], v[132:135], v[232:235], v[32:35]
	v_mfma_f32_16x16x32_bf16 v[24:27], v[140:143], v[232:235], v[24:27]
	v_mfma_f32_16x16x32_bf16 v[24:27], v[136:139], v[228:231], v[24:27]
	v_mfma_f32_16x16x32_bf16 v[20:23], v[144:147], v[228:231], v[20:23]
	v_mfma_f32_16x16x32_bf16 v[20:23], v[148:151], v[232:235], v[20:23]
	v_mfma_f32_16x16x32_bf16 v[12:15], v[184:187], v[232:235], v[12:15]
	v_mfma_f32_16x16x32_bf16 v[12:15], v[180:183], v[228:231], v[12:15]
	v_mfma_f32_16x16x32_bf16 v[0:3], v[180:183], v[236:239], v[0:3]
	v_mfma_f32_16x16x32_bf16 v[0:3], v[184:187], v[240:243], v[0:3]
	v_mfma_f32_16x16x32_bf16 v[4:7], v[148:151], v[240:243], v[4:7]
	v_mfma_f32_16x16x32_bf16 v[4:7], v[144:147], v[236:239], v[4:7]
	v_mfma_f32_16x16x32_bf16 v[8:11], v[136:139], v[236:239], v[8:11]
	v_mfma_f32_16x16x32_bf16 v[8:11], v[140:143], v[240:243], v[8:11]
	v_mfma_f32_16x16x32_bf16 v[16:19], v[132:135], v[240:243], v[16:19]
	v_mfma_f32_16x16x32_bf16 v[16:19], v[128:131], v[236:239], v[16:19]
	s_setprio 0
	s_barrier
	s_add_i32 s34, 0, 0x18000
	s_add_i32 s35, 0, 0x1c000
	v_add_u32_e32 v140, s34, v195
	v_add_u32_e32 v184, s35, v195
	ds_read_b128 v[128:131], v140
	ds_read_b128 v[132:135], v140 offset:1024
	ds_read_b128 v[136:139], v140 offset:2048
	ds_read_b128 v[140:143], v140 offset:3072
	ds_read_b128 v[144:147], v184
	ds_read_b128 v[148:151], v184 offset:1024
	ds_read_b128 v[180:183], v184 offset:2048
	ds_read_b128 v[184:187], v184 offset:3072
	s_add_u32 s30, s30, 0x40000
	s_addc_u32 s31, s31, 0
	s_mov_b32 m0, s51
	ds_read_b128 v[188:191], v200 offset:32768
	ds_read_b128 v[202:205], v200 offset:33792
	ds_read_b128 v[206:209], v200 offset:34816
	ds_read_b128 v[210:213], v200 offset:35840
	ds_read_b128 v[228:231], v200 offset:36864
	ds_read_b128 v[232:235], v200 offset:37888
	ds_read_b128 v[236:239], v200 offset:38912
	ds_read_b128 v[240:243], v200 offset:39936
	global_load_lds_dwordx4 v156, s[30:31]
	s_mov_b32 m0, s52
	s_nop 0
	global_load_lds_dwordx4 v154, s[30:31]
	s_waitcnt vmcnt(8)
	s_waitcnt lgkmcnt(0)
	s_barrier
	s_setprio 1
	s_waitcnt lgkmcnt(0)
	v_mfma_f32_16x16x32_bf16 v[124:127], v[128:131], v[188:191], v[124:127]
	v_mfma_f32_16x16x32_bf16 v[124:127], v[132:135], v[202:205], v[124:127]
	v_mfma_f32_16x16x32_bf16 v[120:123], v[140:143], v[202:205], v[120:123]
	v_mfma_f32_16x16x32_bf16 v[120:123], v[136:139], v[188:191], v[120:123]
	v_mfma_f32_16x16x32_bf16 v[116:119], v[144:147], v[188:191], v[116:119]
	v_mfma_f32_16x16x32_bf16 v[116:119], v[148:151], v[202:205], v[116:119]
	v_mfma_f32_16x16x32_bf16 v[108:111], v[184:187], v[202:205], v[108:111]
	v_mfma_f32_16x16x32_bf16 v[108:111], v[180:183], v[188:191], v[108:111]
	v_mfma_f32_16x16x32_bf16 v[92:95], v[180:183], v[206:209], v[92:95]
	v_mfma_f32_16x16x32_bf16 v[92:95], v[184:187], v[210:213], v[92:95]
	v_mfma_f32_16x16x32_bf16 v[100:103], v[148:151], v[210:213], v[100:103]
	v_mfma_f32_16x16x32_bf16 v[100:103], v[144:147], v[206:209], v[100:103]
	v_mfma_f32_16x16x32_bf16 v[104:107], v[136:139], v[206:209], v[104:107]
	v_mfma_f32_16x16x32_bf16 v[104:107], v[140:143], v[210:213], v[104:107]
	v_mfma_f32_16x16x32_bf16 v[112:115], v[132:135], v[210:213], v[112:115]
	v_mfma_f32_16x16x32_bf16 v[112:115], v[128:131], v[206:209], v[112:115]
	v_mfma_f32_16x16x32_bf16 v[96:99], v[128:131], v[228:231], v[96:99]
	v_mfma_f32_16x16x32_bf16 v[96:99], v[132:135], v[232:235], v[96:99]
	v_mfma_f32_16x16x32_bf16 v[88:91], v[140:143], v[232:235], v[88:91]
	v_mfma_f32_16x16x32_bf16 v[88:91], v[136:139], v[228:231], v[88:91]
	v_mfma_f32_16x16x32_bf16 v[84:87], v[144:147], v[228:231], v[84:87]
	v_mfma_f32_16x16x32_bf16 v[84:87], v[148:151], v[232:235], v[84:87]
	v_mfma_f32_16x16x32_bf16 v[76:79], v[184:187], v[232:235], v[76:79]
	v_mfma_f32_16x16x32_bf16 v[76:79], v[180:183], v[228:231], v[76:79]
	v_mfma_f32_16x16x32_bf16 v[64:67], v[180:183], v[236:239], v[64:67]
	v_mfma_f32_16x16x32_bf16 v[64:67], v[184:187], v[240:243], v[64:67]
	v_mfma_f32_16x16x32_bf16 v[68:71], v[148:151], v[240:243], v[68:71]
	v_mfma_f32_16x16x32_bf16 v[68:71], v[144:147], v[236:239], v[68:71]
	v_mfma_f32_16x16x32_bf16 v[72:75], v[136:139], v[236:239], v[72:75]
	v_mfma_f32_16x16x32_bf16 v[72:75], v[140:143], v[240:243], v[72:75]
	v_mfma_f32_16x16x32_bf16 v[80:83], v[132:135], v[240:243], v[80:83]
	v_mfma_f32_16x16x32_bf16 v[80:83], v[128:131], v[236:239], v[80:83]
	s_setprio 0
	s_barrier
	s_add_i32 s30, s34, s45
	s_mov_b32 m0, s30
	ds_read_b128 v[188:191], v200 offset:49152
	ds_read_b128 v[202:205], v200 offset:50176
	ds_read_b128 v[206:209], v200 offset:51200
	ds_read_b128 v[210:213], v200 offset:52224
	ds_read_b128 v[228:231], v200 offset:53248
	ds_read_b128 v[232:235], v200 offset:54272
	ds_read_b128 v[236:239], v200 offset:55296
	ds_read_b128 v[240:243], v200 offset:56320
	global_load_lds_dwordx4 v168, s[98:99]
	s_add_i32 m0, s30, 0x2000
	s_add_u32 s26, s26, 0x40080
	s_addc_u32 s27, s27, 0
	s_add_i32 s30, s35, s45
	global_load_lds_dwordx4 v152, s[98:99]
	s_mov_b32 m0, s30
	s_nop 0
	global_load_lds_dwordx4 v168, s[26:27]
	s_add_i32 m0, s30, 0x2000
	s_nop 0
	global_load_lds_dwordx4 v152, s[26:27]
	s_mov_b32 m0, s24
	s_nop 0
	global_load_lds_dwordx4 v156, s[100:101]
	s_mov_b32 m0, s53
	s_nop 0
	global_load_lds_dwordx4 v154, s[100:101]
	s_waitcnt vmcnt(8)
	s_waitcnt lgkmcnt(0)
	s_barrier
	s_setprio 1
	s_waitcnt lgkmcnt(0)
	v_mfma_f32_16x16x32_bf16 v[60:63], v[128:131], v[188:191], v[60:63]
	v_mfma_f32_16x16x32_bf16 v[60:63], v[132:135], v[202:205], v[60:63]
	v_mfma_f32_16x16x32_bf16 v[56:59], v[140:143], v[202:205], v[56:59]
	v_mfma_f32_16x16x32_bf16 v[56:59], v[136:139], v[188:191], v[56:59]
	v_mfma_f32_16x16x32_bf16 v[52:55], v[144:147], v[188:191], v[52:55]
	v_mfma_f32_16x16x32_bf16 v[52:55], v[148:151], v[202:205], v[52:55]
	v_mfma_f32_16x16x32_bf16 v[44:47], v[184:187], v[202:205], v[44:47]
	v_mfma_f32_16x16x32_bf16 v[44:47], v[180:183], v[188:191], v[44:47]
	v_mfma_f32_16x16x32_bf16 v[28:31], v[180:183], v[206:209], v[28:31]
	v_mfma_f32_16x16x32_bf16 v[28:31], v[184:187], v[210:213], v[28:31]
	v_mfma_f32_16x16x32_bf16 v[36:39], v[148:151], v[210:213], v[36:39]
	v_mfma_f32_16x16x32_bf16 v[36:39], v[144:147], v[206:209], v[36:39]
	v_mfma_f32_16x16x32_bf16 v[40:43], v[136:139], v[206:209], v[40:43]
	v_mfma_f32_16x16x32_bf16 v[40:43], v[140:143], v[210:213], v[40:43]
	v_mfma_f32_16x16x32_bf16 v[48:51], v[132:135], v[210:213], v[48:51]
	v_mfma_f32_16x16x32_bf16 v[48:51], v[128:131], v[206:209], v[48:51]
	v_mfma_f32_16x16x32_bf16 v[32:35], v[128:131], v[228:231], v[32:35]
	v_mfma_f32_16x16x32_bf16 v[32:35], v[132:135], v[232:235], v[32:35]
	v_mfma_f32_16x16x32_bf16 v[24:27], v[140:143], v[232:235], v[24:27]
	v_mfma_f32_16x16x32_bf16 v[24:27], v[136:139], v[228:231], v[24:27]
	v_mfma_f32_16x16x32_bf16 v[20:23], v[144:147], v[228:231], v[20:23]
	v_mfma_f32_16x16x32_bf16 v[20:23], v[148:151], v[232:235], v[20:23]
	v_mfma_f32_16x16x32_bf16 v[12:15], v[184:187], v[232:235], v[12:15]
	v_mfma_f32_16x16x32_bf16 v[12:15], v[180:183], v[228:231], v[12:15]
	v_mfma_f32_16x16x32_bf16 v[0:3], v[180:183], v[236:239], v[0:3]
	v_mfma_f32_16x16x32_bf16 v[0:3], v[184:187], v[240:243], v[0:3]
	v_mfma_f32_16x16x32_bf16 v[4:7], v[148:151], v[240:243], v[4:7]
	v_mfma_f32_16x16x32_bf16 v[4:7], v[144:147], v[236:239], v[4:7]
	v_mfma_f32_16x16x32_bf16 v[8:11], v[136:139], v[236:239], v[8:11]
	v_mfma_f32_16x16x32_bf16 v[8:11], v[140:143], v[240:243], v[8:11]
	v_mfma_f32_16x16x32_bf16 v[16:19], v[132:135], v[240:243], v[16:19]
	v_mfma_f32_16x16x32_bf16 v[16:19], v[128:131], v[236:239], v[16:19]
	s_setprio 0
	s_barrier
	s_add_i32 s59, s59, 2
	s_add_u32 s22, s22, 0x100
	s_addc_u32 s23, s23, 0
	s_add_u32 s57, s57, 0x100
	s_addc_u32 s58, s58, 0
	s_cmp_gt_u32 s59, 13
	s_cbranch_scc0 .LBB0_178
	s_and_b64 vcc, exec, s[10:11]
	s_cbranch_vccz .LBB0_181
	s_barrier

.LBB0_776:
	s_add_u32 s26, s22, 0xfffc0080
	s_addc_u32 s27, s23, -1
	s_add_i32 s36, 0, 0x10000
	s_cmp_eq_u32 s55, 12
	s_cselect_b32 s31, s15, s27
	s_cselect_b32 s30, s51, s26
	s_cselect_b32 s27, s13, s54
	s_cselect_b32 s26, s52, s53
	s_add_i32 s56, 0, 0x14000
	v_add_u32_e32 v140, s36, v204
	v_add_u32_e32 v156, s56, v204
	ds_read_b128 v[128:131], v140
	ds_read_b128 v[132:135], v140 offset:1024
	ds_read_b128 v[136:139], v140 offset:2048
	ds_read_b128 v[140:143], v140 offset:3072
	ds_read_b128 v[144:147], v156
	ds_read_b128 v[148:151], v156 offset:1024
	ds_read_b128 v[152:155], v156 offset:2048
	ds_read_b128 v[156:159], v156 offset:3072
	s_add_i32 m0, s42, 0xc000
	ds_read_b128 v[182:185], v206
	ds_read_b128 v[186:189], v206 offset:1024
	ds_read_b128 v[190:193], v206 offset:2048
	ds_read_b128 v[194:197], v206 offset:3072
	ds_read_b128 v[198:201], v206 offset:4096
	ds_read_b128 v[208:211], v206 offset:5120
	ds_read_b128 v[212:215], v206 offset:6144
	ds_read_b128 v[228:231], v206 offset:7168
	global_load_lds_dwordx4 v166, s[22:23]
	s_add_i32 m0, s42, 0xe000
	s_nop 0
	global_load_lds_dwordx4 v180, s[22:23]
	s_waitcnt vmcnt(8)
	s_waitcnt lgkmcnt(0)
	s_barrier
	s_setprio 1
	s_waitcnt lgkmcnt(0)
	v_mfma_f32_16x16x32_bf16 v[124:127], v[128:131], v[182:185], v[124:127]
	v_mfma_f32_16x16x32_bf16 v[124:127], v[132:135], v[186:189], v[124:127]
	v_mfma_f32_16x16x32_bf16 v[120:123], v[140:143], v[186:189], v[120:123]
	v_mfma_f32_16x16x32_bf16 v[120:123], v[136:139], v[182:185], v[120:123]
	v_mfma_f32_16x16x32_bf16 v[116:119], v[144:147], v[182:185], v[116:119]
	v_mfma_f32_16x16x32_bf16 v[116:119], v[148:151], v[186:189], v[116:119]
	v_mfma_f32_16x16x32_bf16 v[112:115], v[156:159], v[186:189], v[112:115]
	v_mfma_f32_16x16x32_bf16 v[112:115], v[152:155], v[182:185], v[112:115]
	v_mfma_f32_16x16x32_bf16 v[96:99], v[152:155], v[190:193], v[96:99]
	v_mfma_f32_16x16x32_bf16 v[96:99], v[156:159], v[194:197], v[96:99]
	v_mfma_f32_16x16x32_bf16 v[100:103], v[148:151], v[194:197], v[100:103]
	v_mfma_f32_16x16x32_bf16 v[100:103], v[144:147], v[190:193], v[100:103]
	v_mfma_f32_16x16x32_bf16 v[104:107], v[136:139], v[190:193], v[104:107]
	v_mfma_f32_16x16x32_bf16 v[104:107], v[140:143], v[194:197], v[104:107]
	v_mfma_f32_16x16x32_bf16 v[108:111], v[132:135], v[194:197], v[108:111]
	v_mfma_f32_16x16x32_bf16 v[108:111], v[128:131], v[190:193], v[108:111]
	v_mfma_f32_16x16x32_bf16 v[92:95], v[128:131], v[198:201], v[92:95]
	v_mfma_f32_16x16x32_bf16 v[92:95], v[132:135], v[208:211], v[92:95]
	v_mfma_f32_16x16x32_bf16 v[88:91], v[140:143], v[208:211], v[88:91]
	v_mfma_f32_16x16x32_bf16 v[88:91], v[136:139], v[198:201], v[88:91]
	v_mfma_f32_16x16x32_bf16 v[84:87], v[144:147], v[198:201], v[84:87]
	v_mfma_f32_16x16x32_bf16 v[84:87], v[148:151], v[208:211], v[84:87]
	v_mfma_f32_16x16x32_bf16 v[80:83], v[156:159], v[208:211], v[80:83]
	v_mfma_f32_16x16x32_bf16 v[80:83], v[152:155], v[198:201], v[80:83]
	v_mfma_f32_16x16x32_bf16 v[64:67], v[152:155], v[212:215], v[64:67]
	v_mfma_f32_16x16x32_bf16 v[64:67], v[156:159], v[228:231], v[64:67]
	v_mfma_f32_16x16x32_bf16 v[68:71], v[148:151], v[228:231], v[68:71]
	v_mfma_f32_16x16x32_bf16 v[68:71], v[144:147], v[212:215], v[68:71]
	v_mfma_f32_16x16x32_bf16 v[72:75], v[136:139], v[212:215], v[72:75]
	v_mfma_f32_16x16x32_bf16 v[72:75], v[140:143], v[228:231], v[72:75]
	v_mfma_f32_16x16x32_bf16 v[76:79], v[132:135], v[228:231], v[76:79]
	v_mfma_f32_16x16x32_bf16 v[76:79], v[128:131], v[212:215], v[76:79]
	s_setprio 0
	s_barrier
	s_add_i32 s36, s36, s35
	s_add_u32 s98, s26, s20
	s_addc_u32 s99, s27, s21
	s_mov_b32 m0, s36
	ds_read_b128 v[182:185], v206 offset:16384
	ds_read_b128 v[186:189], v206 offset:17408
	ds_read_b128 v[190:193], v206 offset:18432
	ds_read_b128 v[194:197], v206 offset:19456
	ds_read_b128 v[198:201], v206 offset:20480
	ds_read_b128 v[208:211], v206 offset:21504
	ds_read_b128 v[212:215], v206 offset:22528
	ds_read_b128 v[228:231], v206 offset:23552
	global_load_lds_dwordx4 v168, s[26:27]
	s_add_i32 m0, s36, 0x2000
	s_add_u32 s36, s26, 0x40000
	s_addc_u32 s37, s27, 0
	s_add_i32 s56, s56, s35
	global_load_lds_dwordx4 v160, s[26:27]
	s_mov_b32 m0, s56
	s_nop 0
	global_load_lds_dwordx4 v168, s[36:37]
	s_add_i32 m0, s56, 0x2000
	s_nop 0
	global_load_lds_dwordx4 v160, s[36:37]
	s_add_u32 s100, s30, s20
	s_addc_u32 s101, s31, s21
	s_mov_b32 m0, s42
	s_nop 0
	global_load_lds_dwordx4 v164, s[30:31]
	s_mov_b32 m0, s43
	s_nop 0
	global_load_lds_dwordx4 v162, s[30:31]
	s_waitcnt vmcnt(8)
	s_waitcnt lgkmcnt(0)
	s_barrier
	s_setprio 1
	s_waitcnt lgkmcnt(0)
	v_mfma_f32_16x16x32_bf16 v[60:63], v[128:131], v[182:185], v[60:63]
	v_mfma_f32_16x16x32_bf16 v[60:63], v[132:135], v[186:189], v[60:63]
	v_mfma_f32_16x16x32_bf16 v[56:59], v[140:143], v[186:189], v[56:59]
	v_mfma_f32_16x16x32_bf16 v[56:59], v[136:139], v[182:185], v[56:59]
	v_mfma_f32_16x16x32_bf16 v[52:55], v[144:147], v[182:185], v[52:55]
	v_mfma_f32_16x16x32_bf16 v[52:55], v[148:151], v[186:189], v[52:55]
	v_mfma_f32_16x16x32_bf16 v[48:51], v[156:159], v[186:189], v[48:51]
	v_mfma_f32_16x16x32_bf16 v[48:51], v[152:155], v[182:185], v[48:51]
	v_mfma_f32_16x16x32_bf16 v[32:35], v[152:155], v[190:193], v[32:35]
	v_mfma_f32_16x16x32_bf16 v[32:35], v[156:159], v[194:197], v[32:35]
	v_mfma_f32_16x16x32_bf16 v[36:39], v[148:151], v[194:197], v[36:39]
	v_mfma_f32_16x16x32_bf16 v[36:39], v[144:147], v[190:193], v[36:39]
	v_mfma_f32_16x16x32_bf16 v[40:43], v[136:139], v[190:193], v[40:43]
	v_mfma_f32_16x16x32_bf16 v[40:43], v[140:143], v[194:197], v[40:43]
	v_mfma_f32_16x16x32_bf16 v[44:47], v[132:135], v[194:197], v[44:47]
	v_mfma_f32_16x16x32_bf16 v[44:47], v[128:131], v[190:193], v[44:47]
	v_mfma_f32_16x16x32_bf16 v[28:31], v[128:131], v[198:201], v[28:31]
	v_mfma_f32_16x16x32_bf16 v[28:31], v[132:135], v[208:211], v[28:31]
	v_mfma_f32_16x16x32_bf16 v[24:27], v[140:143], v[208:211], v[24:27]
	v_mfma_f32_16x16x32_bf16 v[24:27], v[136:139], v[198:201], v[24:27]
	v_mfma_f32_16x16x32_bf16 v[20:23], v[144:147], v[198:201], v[20:23]
	v_mfma_f32_16x16x32_bf16 v[20:23], v[148:151], v[208:211], v[20:23]
	v_mfma_f32_16x16x32_bf16 v[16:19], v[156:159], v[208:211], v[16:19]
	v_mfma_f32_16x16x32_bf16 v[16:19], v[152:155], v[198:201], v[16:19]
	v_mfma_f32_16x16x32_bf16 v[0:3], v[152:155], v[212:215], v[0:3]
	v_mfma_f32_16x16x32_bf16 v[0:3], v[156:159], v[228:231], v[0:3]
	v_mfma_f32_16x16x32_bf16 v[4:7], v[148:151], v[228:231], v[4:7]
	v_mfma_f32_16x16x32_bf16 v[4:7], v[144:147], v[212:215], v[4:7]
	v_mfma_f32_16x16x32_bf16 v[8:11], v[136:139], v[212:215], v[8:11]
	v_mfma_f32_16x16x32_bf16 v[8:11], v[140:143], v[228:231], v[8:11]
	v_mfma_f32_16x16x32_bf16 v[12:15], v[132:135], v[228:231], v[12:15]
	v_mfma_f32_16x16x32_bf16 v[12:15], v[128:131], v[212:215], v[12:15]
	s_setprio 0
	s_barrier
	s_add_i32 s36, 0, 0x18000
	s_add_i32 s37, 0, 0x1c000
	v_add_u32_e32 v140, s36, v204
	v_add_u32_e32 v156, s37, v204
	ds_read_b128 v[128:131], v140
	ds_read_b128 v[132:135], v140 offset:1024
	ds_read_b128 v[136:139], v140 offset:2048
	ds_read_b128 v[140:143], v140 offset:3072
	ds_read_b128 v[144:147], v156
	ds_read_b128 v[148:151], v156 offset:1024
	ds_read_b128 v[152:155], v156 offset:2048
	ds_read_b128 v[156:159], v156 offset:3072
	s_add_u32 s30, s30, 0x40000
	s_addc_u32 s31, s31, 0
	s_mov_b32 m0, s44
	ds_read_b128 v[182:185], v206 offset:32768
	ds_read_b128 v[186:189], v206 offset:33792
	ds_read_b128 v[190:193], v206 offset:34816
	ds_read_b128 v[194:197], v206 offset:35840
	ds_read_b128 v[198:201], v206 offset:36864
	ds_read_b128 v[208:211], v206 offset:37888
	ds_read_b128 v[212:215], v206 offset:38912
	ds_read_b128 v[228:231], v206 offset:39936
	global_load_lds_dwordx4 v164, s[30:31]
	s_mov_b32 m0, s45
	s_nop 0
	global_load_lds_dwordx4 v162, s[30:31]
	s_waitcnt vmcnt(8)
	s_waitcnt lgkmcnt(0)
	s_barrier
	s_setprio 1
	s_waitcnt lgkmcnt(0)
	v_mfma_f32_16x16x32_bf16 v[124:127], v[128:131], v[182:185], v[124:127]
	v_mfma_f32_16x16x32_bf16 v[124:127], v[132:135], v[186:189], v[124:127]
	v_mfma_f32_16x16x32_bf16 v[120:123], v[140:143], v[186:189], v[120:123]
	v_mfma_f32_16x16x32_bf16 v[120:123], v[136:139], v[182:185], v[120:123]
	v_mfma_f32_16x16x32_bf16 v[116:119], v[144:147], v[182:185], v[116:119]
	v_mfma_f32_16x16x32_bf16 v[116:119], v[148:151], v[186:189], v[116:119]
	v_mfma_f32_16x16x32_bf16 v[112:115], v[156:159], v[186:189], v[112:115]
	v_mfma_f32_16x16x32_bf16 v[112:115], v[152:155], v[182:185], v[112:115]
	v_mfma_f32_16x16x32_bf16 v[96:99], v[152:155], v[190:193], v[96:99]
	v_mfma_f32_16x16x32_bf16 v[96:99], v[156:159], v[194:197], v[96:99]
	v_mfma_f32_16x16x32_bf16 v[100:103], v[148:151], v[194:197], v[100:103]
	v_mfma_f32_16x16x32_bf16 v[100:103], v[144:147], v[190:193], v[100:103]
	v_mfma_f32_16x16x32_bf16 v[104:107], v[136:139], v[190:193], v[104:107]
	v_mfma_f32_16x16x32_bf16 v[104:107], v[140:143], v[194:197], v[104:107]
	v_mfma_f32_16x16x32_bf16 v[108:111], v[132:135], v[194:197], v[108:111]
	v_mfma_f32_16x16x32_bf16 v[108:111], v[128:131], v[190:193], v[108:111]
	v_mfma_f32_16x16x32_bf16 v[92:95], v[128:131], v[198:201], v[92:95]
	v_mfma_f32_16x16x32_bf16 v[92:95], v[132:135], v[208:211], v[92:95]
	v_mfma_f32_16x16x32_bf16 v[88:91], v[140:143], v[208:211], v[88:91]
	v_mfma_f32_16x16x32_bf16 v[88:91], v[136:139], v[198:201], v[88:91]
	v_mfma_f32_16x16x32_bf16 v[84:87], v[144:147], v[198:201], v[84:87]
	v_mfma_f32_16x16x32_bf16 v[84:87], v[148:151], v[208:211], v[84:87]
	v_mfma_f32_16x16x32_bf16 v[80:83], v[156:159], v[208:211], v[80:83]
	v_mfma_f32_16x16x32_bf16 v[80:83], v[152:155], v[198:201], v[80:83]
	v_mfma_f32_16x16x32_bf16 v[64:67], v[152:155], v[212:215], v[64:67]
	v_mfma_f32_16x16x32_bf16 v[64:67], v[156:159], v[228:231], v[64:67]
	v_mfma_f32_16x16x32_bf16 v[68:71], v[148:151], v[228:231], v[68:71]
	v_mfma_f32_16x16x32_bf16 v[68:71], v[144:147], v[212:215], v[68:71]
	v_mfma_f32_16x16x32_bf16 v[72:75], v[136:139], v[212:215], v[72:75]
	v_mfma_f32_16x16x32_bf16 v[72:75], v[140:143], v[228:231], v[72:75]
	v_mfma_f32_16x16x32_bf16 v[76:79], v[132:135], v[228:231], v[76:79]
	v_mfma_f32_16x16x32_bf16 v[76:79], v[128:131], v[212:215], v[76:79]
	s_setprio 0
	s_barrier
	s_add_i32 s30, s36, s35
	s_mov_b32 m0, s30
	ds_read_b128 v[182:185], v206 offset:49152
	ds_read_b128 v[186:189], v206 offset:50176
	ds_read_b128 v[190:193], v206 offset:51200
	ds_read_b128 v[194:197], v206 offset:52224
	ds_read_b128 v[198:201], v206 offset:53248
	ds_read_b128 v[208:211], v206 offset:54272
	ds_read_b128 v[212:215], v206 offset:55296
	ds_read_b128 v[228:231], v206 offset:56320
	global_load_lds_dwordx4 v168, s[98:99]
	s_add_i32 m0, s30, 0x2000
	s_add_u32 s26, s26, 0x40080
	s_addc_u32 s27, s27, 0
	s_add_i32 s30, s37, s35
	global_load_lds_dwordx4 v160, s[98:99]
	s_mov_b32 m0, s30
	s_nop 0
	global_load_lds_dwordx4 v168, s[26:27]
	s_add_i32 m0, s30, 0x2000
	s_nop 0
	global_load_lds_dwordx4 v160, s[26:27]
	s_mov_b32 m0, s47
	s_nop 0
	global_load_lds_dwordx4 v164, s[100:101]
	s_mov_b32 m0, s48
	s_nop 0
	global_load_lds_dwordx4 v162, s[100:101]
	s_waitcnt vmcnt(8)
	s_waitcnt lgkmcnt(0)
	s_barrier
	s_setprio 1
	s_waitcnt lgkmcnt(0)
	v_mfma_f32_16x16x32_bf16 v[60:63], v[128:131], v[182:185], v[60:63]
	v_mfma_f32_16x16x32_bf16 v[60:63], v[132:135], v[186:189], v[60:63]
	v_mfma_f32_16x16x32_bf16 v[56:59], v[140:143], v[186:189], v[56:59]
	v_mfma_f32_16x16x32_bf16 v[56:59], v[136:139], v[182:185], v[56:59]
	v_mfma_f32_16x16x32_bf16 v[52:55], v[144:147], v[182:185], v[52:55]
	v_mfma_f32_16x16x32_bf16 v[52:55], v[148:151], v[186:189], v[52:55]
	v_mfma_f32_16x16x32_bf16 v[48:51], v[156:159], v[186:189], v[48:51]
	v_mfma_f32_16x16x32_bf16 v[48:51], v[152:155], v[182:185], v[48:51]
	v_mfma_f32_16x16x32_bf16 v[32:35], v[152:155], v[190:193], v[32:35]
	v_mfma_f32_16x16x32_bf16 v[32:35], v[156:159], v[194:197], v[32:35]
	v_mfma_f32_16x16x32_bf16 v[36:39], v[148:151], v[194:197], v[36:39]
	v_mfma_f32_16x16x32_bf16 v[36:39], v[144:147], v[190:193], v[36:39]
	v_mfma_f32_16x16x32_bf16 v[40:43], v[136:139], v[190:193], v[40:43]
	v_mfma_f32_16x16x32_bf16 v[40:43], v[140:143], v[194:197], v[40:43]
	v_mfma_f32_16x16x32_bf16 v[44:47], v[132:135], v[194:197], v[44:47]
	v_mfma_f32_16x16x32_bf16 v[44:47], v[128:131], v[190:193], v[44:47]
	v_mfma_f32_16x16x32_bf16 v[28:31], v[128:131], v[198:201], v[28:31]
	v_mfma_f32_16x16x32_bf16 v[28:31], v[132:135], v[208:211], v[28:31]
	v_mfma_f32_16x16x32_bf16 v[24:27], v[140:143], v[208:211], v[24:27]
	v_mfma_f32_16x16x32_bf16 v[24:27], v[136:139], v[198:201], v[24:27]
	v_mfma_f32_16x16x32_bf16 v[20:23], v[144:147], v[198:201], v[20:23]
	v_mfma_f32_16x16x32_bf16 v[20:23], v[148:151], v[208:211], v[20:23]
	v_mfma_f32_16x16x32_bf16 v[16:19], v[156:159], v[208:211], v[16:19]
	v_mfma_f32_16x16x32_bf16 v[16:19], v[152:155], v[198:201], v[16:19]
	v_mfma_f32_16x16x32_bf16 v[0:3], v[152:155], v[212:215], v[0:3]
	v_mfma_f32_16x16x32_bf16 v[0:3], v[156:159], v[228:231], v[0:3]
	v_mfma_f32_16x16x32_bf16 v[4:7], v[148:151], v[228:231], v[4:7]
	v_mfma_f32_16x16x32_bf16 v[4:7], v[144:147], v[212:215], v[4:7]
	v_mfma_f32_16x16x32_bf16 v[8:11], v[136:139], v[212:215], v[8:11]
	v_mfma_f32_16x16x32_bf16 v[8:11], v[140:143], v[228:231], v[8:11]
	v_mfma_f32_16x16x32_bf16 v[12:15], v[132:135], v[228:231], v[12:15]
	v_mfma_f32_16x16x32_bf16 v[12:15], v[128:131], v[212:215], v[12:15]
	s_setprio 0
	s_barrier
	s_add_i32 s55, s55, 2
	s_add_u32 s22, s22, 0x100
	s_addc_u32 s23, s23, 0
	s_add_u32 s53, s53, 0x100
	s_addc_u32 s54, s54, 0
	s_cmp_gt_u32 s55, 13
	s_cbranch_scc0 .LBB0_776
	s_and_b64 vcc, exec, s[10:11]
	s_cbranch_vccz .LBB0_779
	s_barrier

.LBB0_890:
	s_add_u32 s18, s0, 0xfffc0080
	s_addc_u32 s19, s1, -1
	s_add_i32 s36, 0, 0x10000
	s_cmp_eq_u32 s50, 12
	s_cselect_b32 s23, s13, s19
	s_cselect_b32 s22, s46, s18
	s_cselect_b32 s19, s11, s49
	s_cselect_b32 s18, s47, s48
	s_add_i32 s51, 0, 0x14000
	v_add_u32_e32 v140, s36, v193
	v_add_u32_e32 v180, s51, v193
	ds_read_b128 v[128:131], v140
	ds_read_b128 v[132:135], v140 offset:1024
	ds_read_b128 v[136:139], v140 offset:2048
	ds_read_b128 v[140:143], v140 offset:3072
	ds_read_b128 v[144:147], v180
	ds_read_b128 v[148:151], v180 offset:1024
	ds_read_b128 v[164:167], v180 offset:2048
	ds_read_b128 v[180:183], v180 offset:3072
	s_add_i32 m0, s30, 0xc000
	ds_read_b128 v[184:187], v198
	ds_read_b128 v[188:191], v198 offset:1024
	ds_read_b128 v[200:203], v198 offset:2048
	ds_read_b128 v[204:207], v198 offset:3072
	ds_read_b128 v[208:211], v198 offset:4096
	ds_read_b128 v[212:215], v198 offset:5120
	ds_read_b128 v[228:231], v198 offset:6144
	ds_read_b128 v[232:235], v198 offset:7168
	global_load_lds_dwordx4 v160, s[0:1]
	s_add_i32 m0, s30, 0xe000
	s_nop 0
	global_load_lds_dwordx4 v162, s[0:1]
	s_waitcnt vmcnt(8)
	s_waitcnt lgkmcnt(0)
	s_barrier
	s_setprio 1
	s_waitcnt lgkmcnt(0)
	v_mfma_f32_16x16x32_bf16 v[124:127], v[128:131], v[184:187], v[124:127]
	v_mfma_f32_16x16x32_bf16 v[124:127], v[132:135], v[188:191], v[124:127]
	v_mfma_f32_16x16x32_bf16 v[120:123], v[140:143], v[188:191], v[120:123]
	v_mfma_f32_16x16x32_bf16 v[120:123], v[136:139], v[184:187], v[120:123]
	v_mfma_f32_16x16x32_bf16 v[116:119], v[144:147], v[184:187], v[116:119]
	v_mfma_f32_16x16x32_bf16 v[116:119], v[148:151], v[188:191], v[116:119]
	v_mfma_f32_16x16x32_bf16 v[112:115], v[180:183], v[188:191], v[112:115]
	v_mfma_f32_16x16x32_bf16 v[112:115], v[164:167], v[184:187], v[112:115]
	v_mfma_f32_16x16x32_bf16 v[96:99], v[164:167], v[200:203], v[96:99]
	v_mfma_f32_16x16x32_bf16 v[96:99], v[180:183], v[204:207], v[96:99]
	v_mfma_f32_16x16x32_bf16 v[100:103], v[148:151], v[204:207], v[100:103]
	v_mfma_f32_16x16x32_bf16 v[100:103], v[144:147], v[200:203], v[100:103]
	v_mfma_f32_16x16x32_bf16 v[104:107], v[136:139], v[200:203], v[104:107]
	v_mfma_f32_16x16x32_bf16 v[104:107], v[140:143], v[204:207], v[104:107]
	v_mfma_f32_16x16x32_bf16 v[108:111], v[132:135], v[204:207], v[108:111]
	v_mfma_f32_16x16x32_bf16 v[108:111], v[128:131], v[200:203], v[108:111]
	v_mfma_f32_16x16x32_bf16 v[92:95], v[128:131], v[208:211], v[92:95]
	v_mfma_f32_16x16x32_bf16 v[92:95], v[132:135], v[212:215], v[92:95]
	v_mfma_f32_16x16x32_bf16 v[88:91], v[140:143], v[212:215], v[88:91]
	v_mfma_f32_16x16x32_bf16 v[88:91], v[136:139], v[208:211], v[88:91]
	v_mfma_f32_16x16x32_bf16 v[84:87], v[144:147], v[208:211], v[84:87]
	v_mfma_f32_16x16x32_bf16 v[84:87], v[148:151], v[212:215], v[84:87]
	v_mfma_f32_16x16x32_bf16 v[80:83], v[180:183], v[212:215], v[80:83]
	v_mfma_f32_16x16x32_bf16 v[80:83], v[164:167], v[208:211], v[80:83]
	v_mfma_f32_16x16x32_bf16 v[64:67], v[164:167], v[228:231], v[64:67]
	v_mfma_f32_16x16x32_bf16 v[64:67], v[180:183], v[232:235], v[64:67]
	v_mfma_f32_16x16x32_bf16 v[68:71], v[148:151], v[232:235], v[68:71]
	v_mfma_f32_16x16x32_bf16 v[68:71], v[144:147], v[228:231], v[68:71]
	v_mfma_f32_16x16x32_bf16 v[72:75], v[136:139], v[228:231], v[72:75]
	v_mfma_f32_16x16x32_bf16 v[72:75], v[140:143], v[232:235], v[72:75]
	v_mfma_f32_16x16x32_bf16 v[76:79], v[132:135], v[232:235], v[76:79]
	v_mfma_f32_16x16x32_bf16 v[76:79], v[128:131], v[228:231], v[76:79]
	s_setprio 0
	s_barrier
	s_add_i32 s36, s36, s27
	s_add_u32 s98, s18, s20
	s_addc_u32 s99, s19, s21
	s_mov_b32 m0, s36
	ds_read_b128 v[184:187], v198 offset:16384
	ds_read_b128 v[188:191], v198 offset:17408
	ds_read_b128 v[200:203], v198 offset:18432
	ds_read_b128 v[204:207], v198 offset:19456
	ds_read_b128 v[208:211], v198 offset:20480
	ds_read_b128 v[212:215], v198 offset:21504
	ds_read_b128 v[228:231], v198 offset:22528
	ds_read_b128 v[232:235], v198 offset:23552
	global_load_lds_dwordx4 v168, s[18:19]
	s_add_i32 m0, s36, 0x2000
	s_add_u32 s36, s18, 0x40000
	s_addc_u32 s37, s19, 0
	s_add_i32 s51, s51, s27
	global_load_lds_dwordx4 v152, s[18:19]
	s_mov_b32 m0, s51
	s_nop 0
	global_load_lds_dwordx4 v168, s[36:37]
	s_add_i32 m0, s51, 0x2000
	s_nop 0
	global_load_lds_dwordx4 v152, s[36:37]
	s_add_u32 s100, s22, s20
	s_addc_u32 s101, s23, s21
	s_mov_b32 m0, s30
	s_nop 0
	global_load_lds_dwordx4 v156, s[22:23]
	s_mov_b32 m0, s31
	s_nop 0
	global_load_lds_dwordx4 v154, s[22:23]
	s_waitcnt vmcnt(8)
	s_waitcnt lgkmcnt(0)
	s_barrier
	s_setprio 1
	s_waitcnt lgkmcnt(0)
	v_mfma_f32_16x16x32_bf16 v[60:63], v[128:131], v[184:187], v[60:63]
	v_mfma_f32_16x16x32_bf16 v[60:63], v[132:135], v[188:191], v[60:63]
	v_mfma_f32_16x16x32_bf16 v[56:59], v[140:143], v[188:191], v[56:59]
	v_mfma_f32_16x16x32_bf16 v[56:59], v[136:139], v[184:187], v[56:59]
	v_mfma_f32_16x16x32_bf16 v[52:55], v[144:147], v[184:187], v[52:55]
	v_mfma_f32_16x16x32_bf16 v[52:55], v[148:151], v[188:191], v[52:55]
	v_mfma_f32_16x16x32_bf16 v[48:51], v[180:183], v[188:191], v[48:51]
	v_mfma_f32_16x16x32_bf16 v[48:51], v[164:167], v[184:187], v[48:51]
	v_mfma_f32_16x16x32_bf16 v[32:35], v[164:167], v[200:203], v[32:35]
	v_mfma_f32_16x16x32_bf16 v[32:35], v[180:183], v[204:207], v[32:35]
	v_mfma_f32_16x16x32_bf16 v[36:39], v[148:151], v[204:207], v[36:39]
	v_mfma_f32_16x16x32_bf16 v[36:39], v[144:147], v[200:203], v[36:39]
	v_mfma_f32_16x16x32_bf16 v[40:43], v[136:139], v[200:203], v[40:43]
	v_mfma_f32_16x16x32_bf16 v[40:43], v[140:143], v[204:207], v[40:43]
	v_mfma_f32_16x16x32_bf16 v[44:47], v[132:135], v[204:207], v[44:47]
	v_mfma_f32_16x16x32_bf16 v[44:47], v[128:131], v[200:203], v[44:47]
	v_mfma_f32_16x16x32_bf16 v[28:31], v[128:131], v[208:211], v[28:31]
	v_mfma_f32_16x16x32_bf16 v[28:31], v[132:135], v[212:215], v[28:31]
	v_mfma_f32_16x16x32_bf16 v[24:27], v[140:143], v[212:215], v[24:27]
	v_mfma_f32_16x16x32_bf16 v[24:27], v[136:139], v[208:211], v[24:27]
	v_mfma_f32_16x16x32_bf16 v[20:23], v[144:147], v[208:211], v[20:23]
	v_mfma_f32_16x16x32_bf16 v[20:23], v[148:151], v[212:215], v[20:23]
	v_mfma_f32_16x16x32_bf16 v[16:19], v[180:183], v[212:215], v[16:19]
	v_mfma_f32_16x16x32_bf16 v[16:19], v[164:167], v[208:211], v[16:19]
	v_mfma_f32_16x16x32_bf16 v[0:3], v[164:167], v[228:231], v[0:3]
	v_mfma_f32_16x16x32_bf16 v[0:3], v[180:183], v[232:235], v[0:3]
	v_mfma_f32_16x16x32_bf16 v[4:7], v[148:151], v[232:235], v[4:7]
	v_mfma_f32_16x16x32_bf16 v[4:7], v[144:147], v[228:231], v[4:7]
	v_mfma_f32_16x16x32_bf16 v[8:11], v[136:139], v[228:231], v[8:11]
	v_mfma_f32_16x16x32_bf16 v[8:11], v[140:143], v[232:235], v[8:11]
	v_mfma_f32_16x16x32_bf16 v[12:15], v[132:135], v[232:235], v[12:15]
	v_mfma_f32_16x16x32_bf16 v[12:15], v[128:131], v[228:231], v[12:15]
	s_setprio 0
	s_barrier
	s_add_i32 s36, 0, 0x18000
	s_add_i32 s37, 0, 0x1c000
	v_add_u32_e32 v140, s36, v193
	v_add_u32_e32 v180, s37, v193
	ds_read_b128 v[128:131], v140
	ds_read_b128 v[132:135], v140 offset:1024
	ds_read_b128 v[136:139], v140 offset:2048
	ds_read_b128 v[140:143], v140 offset:3072
	ds_read_b128 v[144:147], v180
	ds_read_b128 v[148:151], v180 offset:1024
	ds_read_b128 v[164:167], v180 offset:2048
	ds_read_b128 v[180:183], v180 offset:3072
	s_add_u32 s22, s22, 0x40000
	s_addc_u32 s23, s23, 0
	s_mov_b32 m0, s34
	ds_read_b128 v[184:187], v198 offset:32768
	ds_read_b128 v[188:191], v198 offset:33792
	ds_read_b128 v[200:203], v198 offset:34816
	ds_read_b128 v[204:207], v198 offset:35840
	ds_read_b128 v[208:211], v198 offset:36864
	ds_read_b128 v[212:215], v198 offset:37888
	ds_read_b128 v[228:231], v198 offset:38912
	ds_read_b128 v[232:235], v198 offset:39936
	global_load_lds_dwordx4 v156, s[22:23]
	s_mov_b32 m0, s35
	s_nop 0
	global_load_lds_dwordx4 v154, s[22:23]
	s_waitcnt vmcnt(8)
	s_waitcnt lgkmcnt(0)
	s_barrier
	s_setprio 1
	s_waitcnt lgkmcnt(0)
	v_mfma_f32_16x16x32_bf16 v[124:127], v[128:131], v[184:187], v[124:127]
	v_mfma_f32_16x16x32_bf16 v[124:127], v[132:135], v[188:191], v[124:127]
	v_mfma_f32_16x16x32_bf16 v[120:123], v[140:143], v[188:191], v[120:123]
	v_mfma_f32_16x16x32_bf16 v[120:123], v[136:139], v[184:187], v[120:123]
	v_mfma_f32_16x16x32_bf16 v[116:119], v[144:147], v[184:187], v[116:119]
	v_mfma_f32_16x16x32_bf16 v[116:119], v[148:151], v[188:191], v[116:119]
	v_mfma_f32_16x16x32_bf16 v[112:115], v[180:183], v[188:191], v[112:115]
	v_mfma_f32_16x16x32_bf16 v[112:115], v[164:167], v[184:187], v[112:115]
	v_mfma_f32_16x16x32_bf16 v[96:99], v[164:167], v[200:203], v[96:99]
	v_mfma_f32_16x16x32_bf16 v[96:99], v[180:183], v[204:207], v[96:99]
	v_mfma_f32_16x16x32_bf16 v[100:103], v[148:151], v[204:207], v[100:103]
	v_mfma_f32_16x16x32_bf16 v[100:103], v[144:147], v[200:203], v[100:103]
	v_mfma_f32_16x16x32_bf16 v[104:107], v[136:139], v[200:203], v[104:107]
	v_mfma_f32_16x16x32_bf16 v[104:107], v[140:143], v[204:207], v[104:107]
	v_mfma_f32_16x16x32_bf16 v[108:111], v[132:135], v[204:207], v[108:111]
	v_mfma_f32_16x16x32_bf16 v[108:111], v[128:131], v[200:203], v[108:111]
	v_mfma_f32_16x16x32_bf16 v[92:95], v[128:131], v[208:211], v[92:95]
	v_mfma_f32_16x16x32_bf16 v[92:95], v[132:135], v[212:215], v[92:95]
	v_mfma_f32_16x16x32_bf16 v[88:91], v[140:143], v[212:215], v[88:91]
	v_mfma_f32_16x16x32_bf16 v[88:91], v[136:139], v[208:211], v[88:91]
	v_mfma_f32_16x16x32_bf16 v[84:87], v[144:147], v[208:211], v[84:87]
	v_mfma_f32_16x16x32_bf16 v[84:87], v[148:151], v[212:215], v[84:87]
	v_mfma_f32_16x16x32_bf16 v[80:83], v[180:183], v[212:215], v[80:83]
	v_mfma_f32_16x16x32_bf16 v[80:83], v[164:167], v[208:211], v[80:83]
	v_mfma_f32_16x16x32_bf16 v[64:67], v[164:167], v[228:231], v[64:67]
	v_mfma_f32_16x16x32_bf16 v[64:67], v[180:183], v[232:235], v[64:67]
	v_mfma_f32_16x16x32_bf16 v[68:71], v[148:151], v[232:235], v[68:71]
	v_mfma_f32_16x16x32_bf16 v[68:71], v[144:147], v[228:231], v[68:71]
	v_mfma_f32_16x16x32_bf16 v[72:75], v[136:139], v[228:231], v[72:75]
	v_mfma_f32_16x16x32_bf16 v[72:75], v[140:143], v[232:235], v[72:75]
	v_mfma_f32_16x16x32_bf16 v[76:79], v[132:135], v[232:235], v[76:79]
	v_mfma_f32_16x16x32_bf16 v[76:79], v[128:131], v[228:231], v[76:79]
	s_setprio 0
	s_barrier
	s_add_i32 s22, s36, s27
	s_mov_b32 m0, s22
	ds_read_b128 v[184:187], v198 offset:49152
	ds_read_b128 v[188:191], v198 offset:50176
	ds_read_b128 v[200:203], v198 offset:51200
	ds_read_b128 v[204:207], v198 offset:52224
	ds_read_b128 v[208:211], v198 offset:53248
	ds_read_b128 v[212:215], v198 offset:54272
	ds_read_b128 v[228:231], v198 offset:55296
	ds_read_b128 v[232:235], v198 offset:56320
	global_load_lds_dwordx4 v168, s[98:99]
	s_add_i32 m0, s22, 0x2000
	s_add_u32 s18, s18, 0x40080
	s_addc_u32 s19, s19, 0
	s_add_i32 s22, s37, s27
	global_load_lds_dwordx4 v152, s[98:99]
	s_mov_b32 m0, s22
	s_nop 0
	global_load_lds_dwordx4 v168, s[18:19]
	s_add_i32 m0, s22, 0x2000
	s_nop 0
	global_load_lds_dwordx4 v152, s[18:19]
	s_mov_b32 m0, s24
	s_nop 0
	global_load_lds_dwordx4 v156, s[100:101]
	s_mov_b32 m0, s42
	s_nop 0
	global_load_lds_dwordx4 v154, s[100:101]
	s_waitcnt vmcnt(8)
	s_waitcnt lgkmcnt(0)
	s_barrier
	s_setprio 1
	s_waitcnt lgkmcnt(0)
	v_mfma_f32_16x16x32_bf16 v[60:63], v[128:131], v[184:187], v[60:63]
	v_mfma_f32_16x16x32_bf16 v[60:63], v[132:135], v[188:191], v[60:63]
	v_mfma_f32_16x16x32_bf16 v[56:59], v[140:143], v[188:191], v[56:59]
	v_mfma_f32_16x16x32_bf16 v[56:59], v[136:139], v[184:187], v[56:59]
	v_mfma_f32_16x16x32_bf16 v[52:55], v[144:147], v[184:187], v[52:55]
	v_mfma_f32_16x16x32_bf16 v[52:55], v[148:151], v[188:191], v[52:55]
	v_mfma_f32_16x16x32_bf16 v[48:51], v[180:183], v[188:191], v[48:51]
	v_mfma_f32_16x16x32_bf16 v[48:51], v[164:167], v[184:187], v[48:51]
	v_mfma_f32_16x16x32_bf16 v[32:35], v[164:167], v[200:203], v[32:35]
	v_mfma_f32_16x16x32_bf16 v[32:35], v[180:183], v[204:207], v[32:35]
	v_mfma_f32_16x16x32_bf16 v[36:39], v[148:151], v[204:207], v[36:39]
	v_mfma_f32_16x16x32_bf16 v[36:39], v[144:147], v[200:203], v[36:39]
	v_mfma_f32_16x16x32_bf16 v[40:43], v[136:139], v[200:203], v[40:43]
	v_mfma_f32_16x16x32_bf16 v[40:43], v[140:143], v[204:207], v[40:43]
	v_mfma_f32_16x16x32_bf16 v[44:47], v[132:135], v[204:207], v[44:47]
	v_mfma_f32_16x16x32_bf16 v[44:47], v[128:131], v[200:203], v[44:47]
	v_mfma_f32_16x16x32_bf16 v[28:31], v[128:131], v[208:211], v[28:31]
	v_mfma_f32_16x16x32_bf16 v[28:31], v[132:135], v[212:215], v[28:31]
	v_mfma_f32_16x16x32_bf16 v[24:27], v[140:143], v[212:215], v[24:27]
	v_mfma_f32_16x16x32_bf16 v[24:27], v[136:139], v[208:211], v[24:27]
	v_mfma_f32_16x16x32_bf16 v[20:23], v[144:147], v[208:211], v[20:23]
	v_mfma_f32_16x16x32_bf16 v[20:23], v[148:151], v[212:215], v[20:23]
	v_mfma_f32_16x16x32_bf16 v[16:19], v[180:183], v[212:215], v[16:19]
	v_mfma_f32_16x16x32_bf16 v[16:19], v[164:167], v[208:211], v[16:19]
	v_mfma_f32_16x16x32_bf16 v[0:3], v[164:167], v[228:231], v[0:3]
	v_mfma_f32_16x16x32_bf16 v[0:3], v[180:183], v[232:235], v[0:3]
	v_mfma_f32_16x16x32_bf16 v[4:7], v[148:151], v[232:235], v[4:7]
	v_mfma_f32_16x16x32_bf16 v[4:7], v[144:147], v[228:231], v[4:7]
	v_mfma_f32_16x16x32_bf16 v[8:11], v[136:139], v[228:231], v[8:11]
	v_mfma_f32_16x16x32_bf16 v[8:11], v[140:143], v[232:235], v[8:11]
	v_mfma_f32_16x16x32_bf16 v[12:15], v[132:135], v[232:235], v[12:15]
	v_mfma_f32_16x16x32_bf16 v[12:15], v[128:131], v[228:231], v[12:15]
	s_setprio 0
	s_barrier
	s_add_i32 s50, s50, 2
	s_add_u32 s0, s0, 0x100
	s_addc_u32 s1, s1, 0
	s_add_u32 s48, s48, 0x100
	s_addc_u32 s49, s49, 0
	s_cmp_gt_u32 s50, 13
	s_cbranch_scc0 .LBB0_890
	s_and_b64 vcc, exec, s[8:9]
	s_cbranch_vccz .LBB0_893
	s_barrier

.LBB0_986:
	s_add_u32 s34, s8, 0xfff00080
	s_addc_u32 s35, s9, -1
	s_add_i32 s36, 0, 0x10000
	s_cmp_eq_u32 s57, 60
	s_cselect_b32 s41, s23, s35
	s_cselect_b32 s40, s53, s34
	s_cselect_b32 s35, s19, s56
	s_cselect_b32 s34, s54, s55
	s_add_i32 s58, 0, 0x14000
	v_add_u32_e32 v140, s36, v228
	v_add_u32_e32 v156, s58, v228
	ds_read_b128 v[128:131], v140
	ds_read_b128 v[132:135], v140 offset:1024
	ds_read_b128 v[136:139], v140 offset:2048
	ds_read_b128 v[140:143], v140 offset:3072
	ds_read_b128 v[144:147], v156
	ds_read_b128 v[148:151], v156 offset:1024
	ds_read_b128 v[152:155], v156 offset:2048
	ds_read_b128 v[156:159], v156 offset:3072
	s_add_i32 m0, s44, 0xc000
	ds_read_b128 v[160:163], v230
	ds_read_b128 v[164:167], v230 offset:1024
	ds_read_b128 v[190:193], v230 offset:2048
	ds_read_b128 v[194:197], v230 offset:3072
	ds_read_b128 v[198:201], v230 offset:4096
	ds_read_b128 v[202:205], v230 offset:5120
	ds_read_b128 v[206:209], v230 offset:6144
	ds_read_b128 v[210:213], v230 offset:7168
	global_load_lds_dwordx4 v186, s[8:9]
	s_add_i32 m0, s44, 0xe000
	s_nop 0
	global_load_lds_dwordx4 v188, s[8:9]
	s_waitcnt vmcnt(8)
	s_waitcnt lgkmcnt(0)
	s_barrier
	s_setprio 1
	s_waitcnt lgkmcnt(0)
	v_mfma_f32_16x16x32_bf16 v[124:127], v[128:131], v[160:163], v[124:127]
	v_mfma_f32_16x16x32_bf16 v[124:127], v[132:135], v[164:167], v[124:127]
	v_mfma_f32_16x16x32_bf16 v[120:123], v[140:143], v[164:167], v[120:123]
	v_mfma_f32_16x16x32_bf16 v[120:123], v[136:139], v[160:163], v[120:123]
	v_mfma_f32_16x16x32_bf16 v[116:119], v[144:147], v[160:163], v[116:119]
	v_mfma_f32_16x16x32_bf16 v[116:119], v[148:151], v[164:167], v[116:119]
	v_mfma_f32_16x16x32_bf16 v[112:115], v[156:159], v[164:167], v[112:115]
	v_mfma_f32_16x16x32_bf16 v[112:115], v[152:155], v[160:163], v[112:115]
	v_mfma_f32_16x16x32_bf16 v[96:99], v[152:155], v[190:193], v[96:99]
	v_mfma_f32_16x16x32_bf16 v[96:99], v[156:159], v[194:197], v[96:99]
	v_mfma_f32_16x16x32_bf16 v[100:103], v[148:151], v[194:197], v[100:103]
	v_mfma_f32_16x16x32_bf16 v[100:103], v[144:147], v[190:193], v[100:103]
	v_mfma_f32_16x16x32_bf16 v[104:107], v[136:139], v[190:193], v[104:107]
	v_mfma_f32_16x16x32_bf16 v[104:107], v[140:143], v[194:197], v[104:107]
	v_mfma_f32_16x16x32_bf16 v[108:111], v[132:135], v[194:197], v[108:111]
	v_mfma_f32_16x16x32_bf16 v[108:111], v[128:131], v[190:193], v[108:111]
	v_mfma_f32_16x16x32_bf16 v[92:95], v[128:131], v[198:201], v[92:95]
	v_mfma_f32_16x16x32_bf16 v[92:95], v[132:135], v[202:205], v[92:95]
	v_mfma_f32_16x16x32_bf16 v[88:91], v[140:143], v[202:205], v[88:91]
	v_mfma_f32_16x16x32_bf16 v[88:91], v[136:139], v[198:201], v[88:91]
	v_mfma_f32_16x16x32_bf16 v[84:87], v[144:147], v[198:201], v[84:87]
	v_mfma_f32_16x16x32_bf16 v[84:87], v[148:151], v[202:205], v[84:87]
	v_mfma_f32_16x16x32_bf16 v[80:83], v[156:159], v[202:205], v[80:83]
	v_mfma_f32_16x16x32_bf16 v[80:83], v[152:155], v[198:201], v[80:83]
	v_mfma_f32_16x16x32_bf16 v[64:67], v[152:155], v[206:209], v[64:67]
	v_mfma_f32_16x16x32_bf16 v[64:67], v[156:159], v[210:213], v[64:67]
	v_mfma_f32_16x16x32_bf16 v[68:71], v[148:151], v[210:213], v[68:71]
	v_mfma_f32_16x16x32_bf16 v[68:71], v[144:147], v[206:209], v[68:71]
	v_mfma_f32_16x16x32_bf16 v[72:75], v[136:139], v[206:209], v[72:75]
	v_mfma_f32_16x16x32_bf16 v[72:75], v[140:143], v[210:213], v[72:75]
	v_mfma_f32_16x16x32_bf16 v[76:79], v[132:135], v[210:213], v[76:79]
	v_mfma_f32_16x16x32_bf16 v[76:79], v[128:131], v[206:209], v[76:79]
	s_setprio 0
	s_barrier
	s_add_i32 s36, s36, s43
	s_add_u32 s98, s34, s20
	s_addc_u32 s99, s35, s21
	s_mov_b32 m0, s36
	ds_read_b128 v[160:163], v230 offset:16384
	ds_read_b128 v[164:167], v230 offset:17408
	ds_read_b128 v[190:193], v230 offset:18432
	ds_read_b128 v[194:197], v230 offset:19456
	ds_read_b128 v[198:201], v230 offset:20480
	ds_read_b128 v[202:205], v230 offset:21504
	ds_read_b128 v[206:209], v230 offset:22528
	ds_read_b128 v[210:213], v230 offset:23552
	global_load_lds_dwordx4 v168, s[34:35]
	s_add_i32 m0, s36, 0x2000
	s_add_u32 s36, s34, 0x100000
	s_addc_u32 s37, s35, 0
	s_add_i32 s58, s58, s43
	global_load_lds_dwordx4 v180, s[34:35]
	s_mov_b32 m0, s58
	s_nop 0
	global_load_lds_dwordx4 v168, s[36:37]
	s_add_i32 m0, s58, 0x2000
	s_nop 0
	global_load_lds_dwordx4 v180, s[36:37]
	s_add_u32 s100, s40, s20
	s_addc_u32 s101, s41, s21
	s_mov_b32 m0, s44
	s_nop 0
	global_load_lds_dwordx4 v184, s[40:41]
	s_mov_b32 m0, s45
	s_nop 0
	global_load_lds_dwordx4 v182, s[40:41]
	s_waitcnt vmcnt(8)
	s_waitcnt lgkmcnt(0)
	s_barrier
	s_setprio 1
	s_waitcnt lgkmcnt(0)
	v_mfma_f32_16x16x32_bf16 v[60:63], v[128:131], v[160:163], v[60:63]
	v_mfma_f32_16x16x32_bf16 v[60:63], v[132:135], v[164:167], v[60:63]
	v_mfma_f32_16x16x32_bf16 v[56:59], v[140:143], v[164:167], v[56:59]
	v_mfma_f32_16x16x32_bf16 v[56:59], v[136:139], v[160:163], v[56:59]
	v_mfma_f32_16x16x32_bf16 v[52:55], v[144:147], v[160:163], v[52:55]
	v_mfma_f32_16x16x32_bf16 v[52:55], v[148:151], v[164:167], v[52:55]
	v_mfma_f32_16x16x32_bf16 v[48:51], v[156:159], v[164:167], v[48:51]
	v_mfma_f32_16x16x32_bf16 v[48:51], v[152:155], v[160:163], v[48:51]
	v_mfma_f32_16x16x32_bf16 v[32:35], v[152:155], v[190:193], v[32:35]
	v_mfma_f32_16x16x32_bf16 v[32:35], v[156:159], v[194:197], v[32:35]
	v_mfma_f32_16x16x32_bf16 v[36:39], v[148:151], v[194:197], v[36:39]
	v_mfma_f32_16x16x32_bf16 v[36:39], v[144:147], v[190:193], v[36:39]
	v_mfma_f32_16x16x32_bf16 v[40:43], v[136:139], v[190:193], v[40:43]
	v_mfma_f32_16x16x32_bf16 v[40:43], v[140:143], v[194:197], v[40:43]
	v_mfma_f32_16x16x32_bf16 v[44:47], v[132:135], v[194:197], v[44:47]
	v_mfma_f32_16x16x32_bf16 v[44:47], v[128:131], v[190:193], v[44:47]
	v_mfma_f32_16x16x32_bf16 v[28:31], v[128:131], v[198:201], v[28:31]
	v_mfma_f32_16x16x32_bf16 v[28:31], v[132:135], v[202:205], v[28:31]
	v_mfma_f32_16x16x32_bf16 v[24:27], v[140:143], v[202:205], v[24:27]
	v_mfma_f32_16x16x32_bf16 v[24:27], v[136:139], v[198:201], v[24:27]
	v_mfma_f32_16x16x32_bf16 v[20:23], v[144:147], v[198:201], v[20:23]
	v_mfma_f32_16x16x32_bf16 v[20:23], v[148:151], v[202:205], v[20:23]
	v_mfma_f32_16x16x32_bf16 v[16:19], v[156:159], v[202:205], v[16:19]
	v_mfma_f32_16x16x32_bf16 v[16:19], v[152:155], v[198:201], v[16:19]
	v_mfma_f32_16x16x32_bf16 v[0:3], v[152:155], v[206:209], v[0:3]
	v_mfma_f32_16x16x32_bf16 v[0:3], v[156:159], v[210:213], v[0:3]
	v_mfma_f32_16x16x32_bf16 v[4:7], v[148:151], v[210:213], v[4:7]
	v_mfma_f32_16x16x32_bf16 v[4:7], v[144:147], v[206:209], v[4:7]
	v_mfma_f32_16x16x32_bf16 v[8:11], v[136:139], v[206:209], v[8:11]
	v_mfma_f32_16x16x32_bf16 v[8:11], v[140:143], v[210:213], v[8:11]
	v_mfma_f32_16x16x32_bf16 v[12:15], v[132:135], v[210:213], v[12:15]
	v_mfma_f32_16x16x32_bf16 v[12:15], v[128:131], v[206:209], v[12:15]
	s_setprio 0
	s_barrier
	s_add_i32 s58, 0, 0x18000
	s_add_i32 s59, 0, 0x1c000
	v_add_u32_e32 v140, s58, v228
	v_add_u32_e32 v156, s59, v228
	ds_read_b128 v[128:131], v140
	ds_read_b128 v[132:135], v140 offset:1024
	ds_read_b128 v[136:139], v140 offset:2048
	ds_read_b128 v[140:143], v140 offset:3072
	ds_read_b128 v[144:147], v156
	ds_read_b128 v[148:151], v156 offset:1024
	ds_read_b128 v[152:155], v156 offset:2048
	ds_read_b128 v[156:159], v156 offset:3072
	s_add_u32 s36, s40, 0x100000
	s_addc_u32 s37, s41, 0
	s_mov_b32 m0, s46
	ds_read_b128 v[160:163], v230 offset:32768
	ds_read_b128 v[164:167], v230 offset:33792
	ds_read_b128 v[190:193], v230 offset:34816
	ds_read_b128 v[194:197], v230 offset:35840
	ds_read_b128 v[198:201], v230 offset:36864
	ds_read_b128 v[202:205], v230 offset:37888
	ds_read_b128 v[206:209], v230 offset:38912
	ds_read_b128 v[210:213], v230 offset:39936
	global_load_lds_dwordx4 v184, s[36:37]
	s_mov_b32 m0, s47
	s_nop 0
	global_load_lds_dwordx4 v182, s[36:37]
	s_waitcnt vmcnt(8)
	s_waitcnt lgkmcnt(0)
	s_barrier
	s_setprio 1
	s_waitcnt lgkmcnt(0)
	v_mfma_f32_16x16x32_bf16 v[124:127], v[128:131], v[160:163], v[124:127]
	v_mfma_f32_16x16x32_bf16 v[124:127], v[132:135], v[164:167], v[124:127]
	v_mfma_f32_16x16x32_bf16 v[120:123], v[140:143], v[164:167], v[120:123]
	v_mfma_f32_16x16x32_bf16 v[120:123], v[136:139], v[160:163], v[120:123]
	v_mfma_f32_16x16x32_bf16 v[116:119], v[144:147], v[160:163], v[116:119]
	v_mfma_f32_16x16x32_bf16 v[116:119], v[148:151], v[164:167], v[116:119]
	v_mfma_f32_16x16x32_bf16 v[112:115], v[156:159], v[164:167], v[112:115]
	v_mfma_f32_16x16x32_bf16 v[112:115], v[152:155], v[160:163], v[112:115]
	v_mfma_f32_16x16x32_bf16 v[96:99], v[152:155], v[190:193], v[96:99]
	v_mfma_f32_16x16x32_bf16 v[96:99], v[156:159], v[194:197], v[96:99]
	v_mfma_f32_16x16x32_bf16 v[100:103], v[148:151], v[194:197], v[100:103]
	v_mfma_f32_16x16x32_bf16 v[100:103], v[144:147], v[190:193], v[100:103]
	v_mfma_f32_16x16x32_bf16 v[104:107], v[136:139], v[190:193], v[104:107]
	v_mfma_f32_16x16x32_bf16 v[104:107], v[140:143], v[194:197], v[104:107]
	v_mfma_f32_16x16x32_bf16 v[108:111], v[132:135], v[194:197], v[108:111]
	v_mfma_f32_16x16x32_bf16 v[108:111], v[128:131], v[190:193], v[108:111]
	v_mfma_f32_16x16x32_bf16 v[92:95], v[128:131], v[198:201], v[92:95]
	v_mfma_f32_16x16x32_bf16 v[92:95], v[132:135], v[202:205], v[92:95]
	v_mfma_f32_16x16x32_bf16 v[88:91], v[140:143], v[202:205], v[88:91]
	v_mfma_f32_16x16x32_bf16 v[88:91], v[136:139], v[198:201], v[88:91]
	v_mfma_f32_16x16x32_bf16 v[84:87], v[144:147], v[198:201], v[84:87]
	v_mfma_f32_16x16x32_bf16 v[84:87], v[148:151], v[202:205], v[84:87]
	v_mfma_f32_16x16x32_bf16 v[80:83], v[156:159], v[202:205], v[80:83]
	v_mfma_f32_16x16x32_bf16 v[80:83], v[152:155], v[198:201], v[80:83]
	v_mfma_f32_16x16x32_bf16 v[64:67], v[152:155], v[206:209], v[64:67]
	v_mfma_f32_16x16x32_bf16 v[64:67], v[156:159], v[210:213], v[64:67]
	v_mfma_f32_16x16x32_bf16 v[68:71], v[148:151], v[210:213], v[68:71]
	v_mfma_f32_16x16x32_bf16 v[68:71], v[144:147], v[206:209], v[68:71]
	v_mfma_f32_16x16x32_bf16 v[72:75], v[136:139], v[206:209], v[72:75]
	v_mfma_f32_16x16x32_bf16 v[72:75], v[140:143], v[210:213], v[72:75]
	v_mfma_f32_16x16x32_bf16 v[76:79], v[132:135], v[210:213], v[76:79]
	v_mfma_f32_16x16x32_bf16 v[76:79], v[128:131], v[206:209], v[76:79]
	s_setprio 0
	s_barrier
	s_add_i32 s36, s58, s43
	s_mov_b32 m0, s36
	ds_read_b128 v[160:163], v230 offset:49152
	ds_read_b128 v[164:167], v230 offset:50176
	ds_read_b128 v[190:193], v230 offset:51200
	ds_read_b128 v[194:197], v230 offset:52224
	ds_read_b128 v[198:201], v230 offset:53248
	ds_read_b128 v[202:205], v230 offset:54272
	ds_read_b128 v[206:209], v230 offset:55296
	ds_read_b128 v[210:213], v230 offset:56320
	global_load_lds_dwordx4 v168, s[98:99]
	s_add_i32 m0, s36, 0x2000
	s_add_u32 s34, s34, 0x100080
	s_addc_u32 s35, s35, 0
	s_add_i32 s36, s59, s43
	global_load_lds_dwordx4 v180, s[98:99]
	s_mov_b32 m0, s36
	s_nop 0
	global_load_lds_dwordx4 v168, s[34:35]
	s_add_i32 m0, s36, 0x2000
	s_nop 0
	global_load_lds_dwordx4 v180, s[34:35]
	s_mov_b32 m0, s50
	s_nop 0
	global_load_lds_dwordx4 v184, s[100:101]
	s_mov_b32 m0, s51
	s_nop 0
	global_load_lds_dwordx4 v182, s[100:101]
	s_waitcnt vmcnt(8)
	s_waitcnt lgkmcnt(0)
	s_barrier
	s_setprio 1
	s_waitcnt lgkmcnt(0)
	v_mfma_f32_16x16x32_bf16 v[60:63], v[128:131], v[160:163], v[60:63]
	v_mfma_f32_16x16x32_bf16 v[60:63], v[132:135], v[164:167], v[60:63]
	v_mfma_f32_16x16x32_bf16 v[56:59], v[140:143], v[164:167], v[56:59]
	v_mfma_f32_16x16x32_bf16 v[56:59], v[136:139], v[160:163], v[56:59]
	v_mfma_f32_16x16x32_bf16 v[52:55], v[144:147], v[160:163], v[52:55]
	v_mfma_f32_16x16x32_bf16 v[52:55], v[148:151], v[164:167], v[52:55]
	v_mfma_f32_16x16x32_bf16 v[48:51], v[156:159], v[164:167], v[48:51]
	v_mfma_f32_16x16x32_bf16 v[48:51], v[152:155], v[160:163], v[48:51]
	v_mfma_f32_16x16x32_bf16 v[32:35], v[152:155], v[190:193], v[32:35]
	v_mfma_f32_16x16x32_bf16 v[32:35], v[156:159], v[194:197], v[32:35]
	v_mfma_f32_16x16x32_bf16 v[36:39], v[148:151], v[194:197], v[36:39]
	v_mfma_f32_16x16x32_bf16 v[36:39], v[144:147], v[190:193], v[36:39]
	v_mfma_f32_16x16x32_bf16 v[40:43], v[136:139], v[190:193], v[40:43]
	v_mfma_f32_16x16x32_bf16 v[40:43], v[140:143], v[194:197], v[40:43]
	v_mfma_f32_16x16x32_bf16 v[44:47], v[132:135], v[194:197], v[44:47]
	v_mfma_f32_16x16x32_bf16 v[44:47], v[128:131], v[190:193], v[44:47]
	v_mfma_f32_16x16x32_bf16 v[28:31], v[128:131], v[198:201], v[28:31]
	v_mfma_f32_16x16x32_bf16 v[28:31], v[132:135], v[202:205], v[28:31]
	v_mfma_f32_16x16x32_bf16 v[24:27], v[140:143], v[202:205], v[24:27]
	v_mfma_f32_16x16x32_bf16 v[24:27], v[136:139], v[198:201], v[24:27]
	v_mfma_f32_16x16x32_bf16 v[20:23], v[144:147], v[198:201], v[20:23]
	v_mfma_f32_16x16x32_bf16 v[20:23], v[148:151], v[202:205], v[20:23]
	v_mfma_f32_16x16x32_bf16 v[16:19], v[156:159], v[202:205], v[16:19]
	v_mfma_f32_16x16x32_bf16 v[16:19], v[152:155], v[198:201], v[16:19]
	v_mfma_f32_16x16x32_bf16 v[0:3], v[152:155], v[206:209], v[0:3]
	v_mfma_f32_16x16x32_bf16 v[0:3], v[156:159], v[210:213], v[0:3]
	v_mfma_f32_16x16x32_bf16 v[4:7], v[148:151], v[210:213], v[4:7]
	v_mfma_f32_16x16x32_bf16 v[4:7], v[144:147], v[206:209], v[4:7]
	v_mfma_f32_16x16x32_bf16 v[8:11], v[136:139], v[206:209], v[8:11]
	v_mfma_f32_16x16x32_bf16 v[8:11], v[140:143], v[210:213], v[8:11]
	v_mfma_f32_16x16x32_bf16 v[12:15], v[132:135], v[210:213], v[12:15]
	v_mfma_f32_16x16x32_bf16 v[12:15], v[128:131], v[206:209], v[12:15]
	s_setprio 0
	s_barrier
	s_add_i32 s57, s57, 2
	s_add_u32 s8, s8, 0x100
	s_addc_u32 s9, s9, 0
	s_add_u32 s55, s55, 0x100
	s_addc_u32 s56, s56, 0
	s_cmp_gt_u32 s57, 61
	s_cbranch_scc0 .LBB0_986
	s_and_b64 vcc, exec, s[12:13]
	s_cbranch_vccz .LBB0_989
	s_barrier
